# lr_phase: A/B loads of the low-rank gate GEMM issued 4 k-steps deep with counted vmcnt (was ~2 loads in flight)
# speedup vs baseline: 1.0021x; 1.0013x over previous
.LBB0_872:
	s_lshl_b32 s9, s12, 6
	v_or_b32_e32 v126, s9, v80
	v_ashrrev_i32_e32 v127, 31, v126
	v_lshlrev_b64 v[118:119], 12, v[126:127]
	v_or_b32_e32 v120, 16, v126
	v_or_b32_e32 v122, 32, v126
	v_or_b32_e32 v124, 48, v126
	v_ashrrev_i32_e32 v121, 31, v120
	v_ashrrev_i32_e32 v123, 31, v122
	v_ashrrev_i32_e32 v125, 31, v124
	v_lshlrev_b64 v[120:121], 12, v[120:121]
	v_lshlrev_b64 v[122:123], 12, v[122:123]
	v_lshlrev_b64 v[124:125], 12, v[124:125]
	v_lshl_add_u64 v[118:119], v[34:35], 0, v[118:119]
	v_lshl_add_u64 v[120:121], v[34:35], 0, v[120:121]
	v_lshl_add_u64 v[122:123], v[34:35], 0, v[122:123]
	v_lshl_add_u64 v[124:125], v[34:35], 0, v[124:125]
	s_mov_b32 s10, 0
	s_mov_b32 s11, 56
	global_load_dword v64, v[4:5], off
	global_load_dword v66, v[4:5], off offset:1024
	global_load_dword v67, v[4:5], off offset:2048
	global_load_dword v65, v[4:5], off offset:3072
	global_load_dword v68, v[6:7], off
	global_load_dword v70, v[8:9], off
	global_load_dword v71, v[10:11], off
	global_load_dword v69, v[12:13], off
	global_load_dword v72, v[14:15], off
	global_load_dword v74, v[16:17], off
	global_load_dword v75, v[18:19], off
	global_load_dword v73, v[20:21], off
	global_load_dword v76, v[22:23], off
	global_load_dword v78, v[24:25], off
	global_load_dword v79, v[26:27], off
	global_load_dword v77, v[28:29], off
	global_load_dword v216, v[0:1], off
	global_load_dwordx4 v[128:131], v[30:31], off
	global_load_dwordx4 v[132:135], v[32:33], off
	global_load_dwordx4 v[136:139], v[118:119], off
	global_load_dwordx4 v[140:143], v[120:121], off
	global_load_dwordx4 v[144:147], v[122:123], off
	global_load_dwordx4 v[148:151], v[124:125], off
	global_load_dwordx4 v[152:155], v[30:31], off offset:64
	global_load_dwordx4 v[156:159], v[32:33], off offset:64
	global_load_dwordx4 v[160:163], v[118:119], off offset:64
	global_load_dwordx4 v[164:167], v[120:121], off offset:64
	global_load_dwordx4 v[168:171], v[122:123], off offset:64
	global_load_dwordx4 v[172:175], v[124:125], off offset:64
	global_load_dwordx4 v[176:179], v[30:31], off offset:128
	global_load_dwordx4 v[180:183], v[32:33], off offset:128
	global_load_dwordx4 v[184:187], v[118:119], off offset:128
	global_load_dwordx4 v[188:191], v[120:121], off offset:128
	global_load_dwordx4 v[192:195], v[122:123], off offset:128
	global_load_dwordx4 v[196:199], v[124:125], off offset:128
	global_load_dwordx4 v[200:203], v[30:31], off offset:192
	global_load_dwordx4 v[204:207], v[32:33], off offset:192
	global_load_dwordx4 v[208:211], v[118:119], off offset:192
	global_load_dwordx4 v[212:215], v[120:121], off offset:192
	global_load_dwordx4 v[218:221], v[122:123], off offset:192
	global_load_dwordx4 v[222:225], v[124:125], off offset:192
	s_waitcnt vmcnt(18)
	v_mfma_f32_16x16x32_bf16 v[86:89], v[136:139], v[128:131], 0
	v_mfma_f32_16x16x32_bf16 v[90:93], v[136:139], v[132:135], 0
	v_mfma_f32_16x16x32_bf16 v[94:97], v[140:143], v[128:131], 0
	v_mfma_f32_16x16x32_bf16 v[98:101], v[140:143], v[132:135], 0
	v_mfma_f32_16x16x32_bf16 v[102:105], v[144:147], v[128:131], 0
	v_mfma_f32_16x16x32_bf16 v[106:109], v[144:147], v[132:135], 0
	v_mfma_f32_16x16x32_bf16 v[110:113], v[148:151], v[128:131], 0
	v_mfma_f32_16x16x32_bf16 v[114:117], v[148:151], v[132:135], 0
	global_load_dwordx4 v[128:131], v[30:31], off offset:256
	global_load_dwordx4 v[132:135], v[32:33], off offset:256
	global_load_dwordx4 v[136:139], v[118:119], off offset:256
	global_load_dwordx4 v[140:143], v[120:121], off offset:256
	global_load_dwordx4 v[144:147], v[122:123], off offset:256
	global_load_dwordx4 v[148:151], v[124:125], off offset:256
	s_waitcnt vmcnt(18)
	v_mfma_f32_16x16x32_bf16 v[86:89], v[160:163], v[152:155], v[86:89]
	v_mfma_f32_16x16x32_bf16 v[90:93], v[160:163], v[156:159], v[90:93]
	v_mfma_f32_16x16x32_bf16 v[94:97], v[164:167], v[152:155], v[94:97]
	v_mfma_f32_16x16x32_bf16 v[98:101], v[164:167], v[156:159], v[98:101]
	v_mfma_f32_16x16x32_bf16 v[102:105], v[168:171], v[152:155], v[102:105]
	v_mfma_f32_16x16x32_bf16 v[106:109], v[168:171], v[156:159], v[106:109]
	v_mfma_f32_16x16x32_bf16 v[110:113], v[172:175], v[152:155], v[110:113]
	v_mfma_f32_16x16x32_bf16 v[114:117], v[172:175], v[156:159], v[114:117]
	global_load_dwordx4 v[152:155], v[30:31], off offset:320
	global_load_dwordx4 v[156:159], v[32:33], off offset:320
	global_load_dwordx4 v[160:163], v[118:119], off offset:320
	global_load_dwordx4 v[164:167], v[120:121], off offset:320
	global_load_dwordx4 v[168:171], v[122:123], off offset:320
	global_load_dwordx4 v[172:175], v[124:125], off offset:320
	s_waitcnt vmcnt(18)
	v_mfma_f32_16x16x32_bf16 v[86:89], v[184:187], v[176:179], v[86:89]
	v_mfma_f32_16x16x32_bf16 v[90:93], v[184:187], v[180:183], v[90:93]
	v_mfma_f32_16x16x32_bf16 v[94:97], v[188:191], v[176:179], v[94:97]
	v_mfma_f32_16x16x32_bf16 v[98:101], v[188:191], v[180:183], v[98:101]
	v_mfma_f32_16x16x32_bf16 v[102:105], v[192:195], v[176:179], v[102:105]
	v_mfma_f32_16x16x32_bf16 v[106:109], v[192:195], v[180:183], v[106:109]
	v_mfma_f32_16x16x32_bf16 v[110:113], v[196:199], v[176:179], v[110:113]
	v_mfma_f32_16x16x32_bf16 v[114:117], v[196:199], v[180:183], v[114:117]
	global_load_dwordx4 v[176:179], v[30:31], off offset:384
	global_load_dwordx4 v[180:183], v[32:33], off offset:384
	global_load_dwordx4 v[184:187], v[118:119], off offset:384
	global_load_dwordx4 v[188:191], v[120:121], off offset:384
	global_load_dwordx4 v[192:195], v[122:123], off offset:384
	global_load_dwordx4 v[196:199], v[124:125], off offset:384
	s_waitcnt vmcnt(18)
	v_mfma_f32_16x16x32_bf16 v[86:89], v[208:211], v[200:203], v[86:89]
	v_mfma_f32_16x16x32_bf16 v[90:93], v[208:211], v[204:207], v[90:93]
	v_mfma_f32_16x16x32_bf16 v[94:97], v[212:215], v[200:203], v[94:97]
	v_mfma_f32_16x16x32_bf16 v[98:101], v[212:215], v[204:207], v[98:101]
	v_mfma_f32_16x16x32_bf16 v[102:105], v[218:221], v[200:203], v[102:105]
	v_mfma_f32_16x16x32_bf16 v[106:109], v[218:221], v[204:207], v[106:109]
	v_mfma_f32_16x16x32_bf16 v[110:113], v[222:225], v[200:203], v[110:113]
	v_mfma_f32_16x16x32_bf16 v[114:117], v[222:225], v[204:207], v[114:117]
	global_load_dwordx4 v[200:203], v[30:31], off offset:448
	global_load_dwordx4 v[204:207], v[32:33], off offset:448
	global_load_dwordx4 v[208:211], v[118:119], off offset:448
	global_load_dwordx4 v[212:215], v[120:121], off offset:448
	global_load_dwordx4 v[218:221], v[122:123], off offset:448
	global_load_dwordx4 v[222:225], v[124:125], off offset:448
	s_waitcnt vmcnt(18)
	v_mfma_f32_16x16x32_bf16 v[86:89], v[136:139], v[128:131], v[86:89]
	v_mfma_f32_16x16x32_bf16 v[90:93], v[136:139], v[132:135], v[90:93]
	v_mfma_f32_16x16x32_bf16 v[94:97], v[140:143], v[128:131], v[94:97]
	v_mfma_f32_16x16x32_bf16 v[98:101], v[140:143], v[132:135], v[98:101]
	v_mfma_f32_16x16x32_bf16 v[102:105], v[144:147], v[128:131], v[102:105]
	v_mfma_f32_16x16x32_bf16 v[106:109], v[144:147], v[132:135], v[106:109]
	v_mfma_f32_16x16x32_bf16 v[110:113], v[148:151], v[128:131], v[110:113]
	v_mfma_f32_16x16x32_bf16 v[114:117], v[148:151], v[132:135], v[114:117]
	s_waitcnt vmcnt(12)
	v_mfma_f32_16x16x32_bf16 v[86:89], v[160:163], v[152:155], v[86:89]
	v_mfma_f32_16x16x32_bf16 v[90:93], v[160:163], v[156:159], v[90:93]
	v_mfma_f32_16x16x32_bf16 v[94:97], v[164:167], v[152:155], v[94:97]
	v_mfma_f32_16x16x32_bf16 v[98:101], v[164:167], v[156:159], v[98:101]
	v_mfma_f32_16x16x32_bf16 v[102:105], v[168:171], v[152:155], v[102:105]
	v_mfma_f32_16x16x32_bf16 v[106:109], v[168:171], v[156:159], v[106:109]
	v_mfma_f32_16x16x32_bf16 v[110:113], v[172:175], v[152:155], v[110:113]
	v_mfma_f32_16x16x32_bf16 v[114:117], v[172:175], v[156:159], v[114:117]
	s_waitcnt vmcnt(6)
	v_mfma_f32_16x16x32_bf16 v[86:89], v[184:187], v[176:179], v[86:89]
	v_mfma_f32_16x16x32_bf16 v[90:93], v[184:187], v[180:183], v[90:93]
	v_mfma_f32_16x16x32_bf16 v[94:97], v[188:191], v[176:179], v[94:97]
	v_mfma_f32_16x16x32_bf16 v[98:101], v[188:191], v[180:183], v[98:101]
	v_mfma_f32_16x16x32_bf16 v[102:105], v[192:195], v[176:179], v[102:105]
	v_mfma_f32_16x16x32_bf16 v[106:109], v[192:195], v[180:183], v[106:109]
	v_mfma_f32_16x16x32_bf16 v[110:113], v[196:199], v[176:179], v[110:113]
	v_mfma_f32_16x16x32_bf16 v[114:117], v[196:199], v[180:183], v[114:117]
	s_waitcnt vmcnt(0)
	v_mfma_f32_16x16x32_bf16 v[86:89], v[208:211], v[200:203], v[86:89]
	v_mfma_f32_16x16x32_bf16 v[90:93], v[208:211], v[204:207], v[90:93]
	v_mfma_f32_16x16x32_bf16 v[94:97], v[212:215], v[200:203], v[94:97]
	v_mfma_f32_16x16x32_bf16 v[98:101], v[212:215], v[204:207], v[98:101]
	v_mfma_f32_16x16x32_bf16 v[102:105], v[218:221], v[200:203], v[102:105]
	v_mfma_f32_16x16x32_bf16 v[106:109], v[218:221], v[204:207], v[106:109]
	v_mfma_f32_16x16x32_bf16 v[110:113], v[222:225], v[200:203], v[110:113]
	v_mfma_f32_16x16x32_bf16 v[114:117], v[222:225], v[204:207], v[114:117]
	v_add_u32_e32 v126, s8, v81
	s_nop 7
	s_nop 3
	ds_write_b128 v126, v[86:89]
	ds_write_b128 v126, v[90:93] offset:1024
	ds_write_b128 v126, v[94:97] offset:2048
	ds_write_b128 v126, v[98:101] offset:3072
	ds_write_b128 v126, v[102:105] offset:4096
	ds_write_b128 v126, v[106:109] offset:5120
	ds_write_b128 v126, v[110:113] offset:6144
	ds_write_b128 v126, v[114:117] offset:7168
	s_waitcnt lgkmcnt(0)
	s_barrier
	ds_read_b128 v[86:89], v82
	ds_read_b128 v[90:93], v83 offset:8192
	ds_read_b128 v[94:97], v83 offset:16384
	ds_read_b128 v[98:101], v83 offset:24576
	ds_read_b128 v[102:105], v83 offset:32768
	ds_read_b128 v[106:109], v83 offset:57344
	s_waitcnt lgkmcnt(4)
	v_pk_add_f32 v[88:89], v[88:89], v[92:93]
	v_pk_add_f32 v[86:87], v[86:87], v[90:91]
	s_waitcnt lgkmcnt(3)
	v_pk_add_f32 v[88:89], v[88:89], v[96:97]
	v_pk_add_f32 v[90:91], v[86:87], v[94:95]
	s_waitcnt lgkmcnt(2)
	v_pk_add_f32 v[94:95], v[88:89], v[100:101]
	ds_read_b128 v[86:89], v83 offset:40960
	v_pk_add_f32 v[96:97], v[90:91], v[98:99]
	ds_read_b128 v[90:93], v83 offset:49152
	s_waitcnt lgkmcnt(3)
	v_pk_add_f32 v[96:97], v[96:97], v[102:103]
	v_pk_add_f32 v[94:95], v[94:95], v[104:105]
	s_waitcnt lgkmcnt(1)
	v_pk_add_f32 v[86:87], v[96:97], v[86:87]
	v_pk_add_f32 v[88:89], v[94:95], v[88:89]
	s_waitcnt lgkmcnt(0)
	v_pk_add_f32 v[86:87], v[86:87], v[90:91]
	v_pk_add_f32 v[88:89], v[88:89], v[92:93]
	v_pk_add_f32 v[86:87], v[86:87], v[106:107]
	v_pk_add_f32 v[88:89], v[88:89], v[108:109]
	ds_write2_b32 v85, v86, v87 offset1:32
	ds_write2_b32 v85, v88, v89 offset0:64 offset1:96
	s_waitcnt lgkmcnt(0)
	s_barrier
	v_mov_b32_e32 v86, 0
	s_waitcnt vmcnt(0)
